# row loops (prologue bf16 conversion of x, final LayerNorm pass): waits count only the prefetch loads, not the acknowledgements of the row just stored
# baseline (speedup 1.0000x reference)
; __device__ __forceinline__ void prologue(const Params& P, LAS unsigned char* lds, int tid_in) {
;     ...
;     float* X = (float*)(ws + WS_X); bf16* XB = (bf16*)(ws + WS_XB);
;     {
;         f32x4 vn[4];
;         auto row_src = [&](int m) -> const float* {
;             if (m < NPT) { const int bb = m / LP, t = m % LP; return t < 16 ? P.in[I_META] + (size_t)t * D : P.in[I_XP] + ((size_t)bb * 2048 + (t - 16)) * D; }
;             if (m < M) return P.in[I_XS] + (size_t)(m - NPT) * D;
;             return nullptr; };
;         if (gw < MP) { const float* src = row_src(gw);
; #pragma unroll
;             for (int j = 0; j < 4; ++j) { vn[j] = (f32x4){0.f, 0.f, 0.f, 0.f}; if (src) vn[j] = *(const f32x4*)(src + 256 * j + 4 * lane); } }
;         for (int m = gw; m < MP; m += NGW) {
.LBB0_85:
	s_or_b64 exec, exec, s[0:1]
	v_ashrrev_i32_e32 v33, 31, v32
	v_lshlrev_b64 v[18:19], 11, v[32:33]
	v_readlane_b32 s8, v252, 1
	v_lshl_or_b32 v18, v16, 3, v18
	v_readlane_b32 s12, v252, 5
	v_readlane_b32 s13, v252, 6
	s_mov_b64 s[0:1], 0xcb00000
	v_readlane_b32 s9, v252, 2
	v_lshl_add_u64 v[16:17], s[12:13], 0, v[18:19]
	v_lshl_add_u64 v[36:37], v[16:17], 0, s[0:1]
	v_readlane_b32 s0, v252, 58
	v_readlane_b32 s1, v252, 59
	v_readlane_b32 s10, v252, 3
	v_readlane_b32 s11, v252, 4
	v_readlane_b32 s14, v252, 7
	v_readlane_b32 s15, v252, 8
	s_mov_b32 s4, s0
	s_ashr_i32 s5, s0, 31
	v_writelane_b32 v252, s0, 58
	s_lshl_b64 s[4:5], s[4:5], 11
	s_mov_b64 s[8:9], 0
	v_writelane_b32 v252, s1, 59
	s_movk_i32 s14, 0x4300
	s_movk_i32 s15, 0x42ff
	s_movk_i32 s16, 0x407f
	s_movk_i32 s17, 0x4280
	v_mov_b32_e32 v39, 0
	s_mov_b32 s18, 0xfe03f81
	v_lshlrev_b32_e32 v38, 2, v4
	s_waitcnt vmcnt(0)
	s_branch .LBB0_88

; __device__ __forceinline__ void prologue(const Params& P, LAS unsigned char* lds, int tid_in) {
;     ...
;         auto row_src = [&](int m) -> const float* {
;             if (m < NPT) { const int bb = m / LP, t = m % LP; return t < 16 ? P.in[I_META] + (size_t)t * D : P.in[I_XP] + ((size_t)bb * 2048 + (t - 16)) * D; }
;             if (m < M) return P.in[I_XS] + (size_t)(m - NPT) * D;
;             return nullptr; };
;     ...
;         for (int m = gw; m < MP; m += NGW) {
;             f32x4 v[4];
; #pragma unroll
;             for (int j = 0; j < 4; ++j) v[j] = vn[j];
;             if (m + NGW < MP) { const float* src = row_src(m + NGW);
; #pragma unroll
;                 for (int j = 0; j < 4; ++j) { vn[j] = (f32x4){0.f, 0.f, 0.f, 0.f}; if (src) vn[j] = *(const f32x4*)(src + 256 * j + 4 * lane); } }
.LBB0_88:
	v_readlane_b32 s0, v252, 58
	v_readlane_b32 s1, v252, 59
	s_nop 0
	v_mov_b32_e32 v27, v11
	v_add_u32_e32 v32, s0, v32
	v_cmp_gt_i32_e64 s[0:1], s14, v32
	v_cmp_lt_i32_e32 vcc, s15, v32
	v_mov_b32_e32 v26, v10
	v_mov_b32_e32 v25, v9
	v_mov_b32_e32 v24, v8
	v_mov_b32_e32 v31, v15
	v_mov_b32_e32 v30, v14
	v_mov_b32_e32 v29, v13
	v_mov_b32_e32 v28, v12
	v_mov_b32_e32 v19, v7
	v_mov_b32_e32 v18, v6
	v_mov_b32_e32 v17, v5
	v_mov_b32_e32 v16, v35
	v_mov_b32_e32 v23, v3
	v_mov_b32_e32 v22, v2
	v_mov_b32_e32 v21, v1
	v_mov_b32_e32 v20, v0
	s_and_saveexec_b64 s[10:11], s[0:1]
	s_cbranch_execz .LBB0_87
	v_cmp_lt_i32_e64 s[0:1], s16, v32
	s_and_saveexec_b64 s[12:13], s[0:1]
	s_xor_b64 s[12:13], exec, s[12:13]
	s_cbranch_execz .LBB0_91
	v_add_u32_e32 v16, 0xffffbf80, v32
	v_mov_b32_e32 v17, v39
	v_readlane_b32 s36, v252, 25
	v_lshlrev_b64 v[16:17], 12, v[16:17]
	v_readlane_b32 s38, v252, 27
	v_readlane_b32 s39, v252, 28
	v_cmp_gt_u32_e64 s[0:1], s17, v32
	v_readlane_b32 s37, v252, 26
	v_lshl_add_u64 v[16:17], s[38:39], 0, v[16:17]
	v_readlane_b32 s40, v252, 29
	v_readlane_b32 s41, v252, 30
	v_readlane_b32 s42, v252, 31
	v_readlane_b32 s43, v252, 32
	v_readlane_b32 s44, v252, 33
	v_readlane_b32 s45, v252, 34
	v_readlane_b32 s46, v252, 35
	v_readlane_b32 s47, v252, 36
	v_readlane_b32 s48, v252, 37
	v_readlane_b32 s49, v252, 38
	v_readlane_b32 s50, v252, 39
	v_readlane_b32 s51, v252, 40
	v_cndmask_b32_e64 v17, 0, v17, s[0:1]
	v_cndmask_b32_e64 v16, 0, v16, s[0:1]

; template <bool FINAL> __device__ __forceinline__ void ln_pass(const Params& P, const float* g, const float* b, int tid_in) {
;     const int tid = tid_in, lane = tid & 63, wave = tid >> 6, gw = blockIdx.x * 8 + wave, NGW = gridDim.x * 8;
;     float* X = (float*)(P.ws + WS_X); bf16* XB = (bf16*)(P.ws + WS_XB);
;     f32x4 gv[4], bv[4];
; #pragma unroll
;     for (int j = 0; j < 4; ++j) { gv[j] = *(const f32x4*)(g + 256 * j + 4 * lane); bv[j] = *(const f32x4*)(b + 256 * j + 4 * lane); }
;     f32x4 vn[4];
;     if (gw < M) {
; #pragma unroll
;         for (int j = 0; j < 4; ++j) vn[j] = *(const f32x4*)(X + (size_t)gw * D + 256 * j + 4 * lane);
;     }
.LBB0_1816:
	v_readlane_b32 s0, v252, 57
	v_ashrrev_i32_e32 v0, 6, v216
	s_movk_i32 s10, 0x4280
	v_add_u32_e32 v68, s0, v0
	v_cmp_gt_i32_e32 vcc, s10, v68
	s_and_saveexec_b64 s[0:1], vcc
	v_readlane_b32 s16, v252, 1
	v_readlane_b32 s17, v252, 2
	v_readlane_b32 s18, v252, 3
	v_readlane_b32 s19, v252, 4
	v_readlane_b32 s20, v252, 5
	v_readlane_b32 s21, v252, 6
	v_readlane_b32 s22, v252, 7
	v_readlane_b32 s23, v252, 8
	s_cbranch_execz .LBB0_1827
	v_lshlrev_b32_e32 v0, 2, v216
	v_and_b32_e32 v48, 0xfc, v0
	v_readlane_b32 s36, v252, 9
	v_mov_b32_e32 v63, 0
	v_lshlrev_b32_e32 v62, 2, v48
	v_readlane_b32 s50, v252, 23
	v_readlane_b32 s51, v252, 24
	s_mov_b64 s[0:1], 0x3000
	v_ashrrev_i32_e32 v69, 31, v68
	v_lshl_add_u64 v[0:1], s[50:51], 0, v[62:63]
	v_lshl_add_u64 v[50:51], v[0:1], 0, s[0:1]
	v_add_co_u32_e32 v0, vcc, 0x3000, v0
	v_lshl_add_u64 v[4:5], s[16:17], 0, v[62:63]
	s_nop 0
	v_addc_co_u32_e32 v1, vcc, 0, v1, vcc
	v_lshlrev_b64 v[12:13], 12, v[68:69]
	v_add_co_u32_e32 v54, vcc, 0x3000, v4
	v_lshl_add_u64 v[12:13], s[96:97], 0, v[12:13]
	v_lshl_add_u64 v[52:53], v[4:5], 0, s[0:1]
	global_load_dwordx4 v[0:3], v[0:1], off
	v_addc_co_u32_e32 v55, vcc, 0, v5, vcc
	global_load_dwordx4 v[4:7], v[50:51], off offset:1024
	global_load_dwordx4 v[8:11], v[50:51], off offset:2048
	v_lshl_add_u64 v[56:57], v[12:13], 0, v[62:63]
	global_load_dwordx4 v[44:47], v[56:57], off
	global_load_dwordx4 v[12:15], v[52:53], off offset:1024
	global_load_dwordx4 v[16:19], v[52:53], off offset:2048
	global_load_dwordx4 v[40:43], v[56:57], off offset:1024
	global_load_dwordx4 v[20:23], v[50:51], off offset:3072
	global_load_dwordx4 v[36:39], v[56:57], off offset:2048
	global_load_dwordx4 v[32:35], v[56:57], off offset:3072
	global_load_dwordx4 v[24:27], v[52:53], off offset:3072
	global_load_dwordx4 v[28:31], v[54:55], off
	s_add_u32 s4, s18, 0x4000000
	s_mov_b64 s[6:7], 0
	s_movk_i32 s11, 0x427f
	s_movk_i32 s12, 0x407f
	s_mov_b32 s13, 0xfe03f81
	v_mov_b32_e32 v69, 0x3727c5ac
	s_mov_b32 s14, 0xf800000
	v_mov_b32_e32 v80, 0x260
	s_addc_u32 s5, s19, 0
	v_lshlrev_b32_e32 v64, 2, v48
	v_lshl_add_u64 v[66:67], s[96:97], 0, v[62:63]
	v_readlane_b32 s37, v252, 10
	v_readlane_b32 s38, v252, 11
	v_readlane_b32 s39, v252, 12
	v_readlane_b32 s40, v252, 13
	v_readlane_b32 s41, v252, 14
	v_readlane_b32 s42, v252, 15
	v_readlane_b32 s43, v252, 16
	v_readlane_b32 s44, v252, 17
	v_readlane_b32 s45, v252, 18
	v_readlane_b32 s46, v252, 19
	v_readlane_b32 s47, v252, 20
	v_readlane_b32 s48, v252, 21
	v_readlane_b32 s49, v252, 22
	s_waitcnt vmcnt(8)
	v_mov_b32_e32 v72, v45
	v_mov_b32_e32 v73, v46
	v_mov_b32_e32 v45, v47
	s_waitcnt vmcnt(5)
	v_mov_b32_e32 v70, v41
	v_mov_b32_e32 v71, v42
	v_mov_b32_e32 v41, v43
	s_waitcnt vmcnt(0)
	v_mov_b32_e32 v74, v33
	v_mov_b32_e32 v42, v35
	s_branch .LBB0_1819

; __device__ __forceinline__ unsigned cvtpk(float lo, float hi) { f32x2_t v = {lo, hi}; bf16x2_t b = __builtin_convertvector(v, bf16x2_t); return __builtin_bit_cast(unsigned, b); }
; template <bool FINAL> __device__ __forceinline__ void ln_pass(const Params& P, const float* g, const float* b, int tid_in) {
;     ...
;         for (int j = 0; j < 4; ++j) { v[j] = vn[j]; s += (v[j][0] + v[j][1]) + (v[j][2] + v[j][3]); }
;         { const int mn = m + NGW < M ? m + NGW : m;
; #pragma unroll
;           for (int j = 0; j < 4; ++j) vn[j] = *(const f32x4*)(X + (size_t)mn * D + 256 * j + 4 * lane); }
;     ...
;         const float rstd = 1.f / sqrtf(q * (1.f / D) + LN_EPS);
;         float* yo = nullptr;
;         if (FINAL) { if (m < NPT) { const int bb = m / LP, t = m % LP; if (t >= 16) yo = P.out + O_YP + ((size_t)bb * 2048 + (t - 16)) * D; } else yo = P.out + O_YS + (size_t)(m - NPT) * D; }
; #pragma unroll
;         for (int j = 0; j < 4; ++j) {
;             const f32x4 y = v[j] * rstd * gv[j] + bv[j];
;             if (FINAL) { if (yo) *(f32x4*)(yo + 256 * j + 4 * lane) = y; }
;             else { *(f32x4*)(X + (size_t)m * D + 256 * j + 4 * lane) = y;
;                    u32x2 w; w.x = cvtpk(y[0], y[1]); w.y = cvtpk(y[2], y[3]); *(u32x2*)(XB + (size_t)m * D + 256 * j + 4 * lane) = w; }
;         }
.LBB0_1826:
	s_waitcnt lgkmcnt(0)
	v_add_f32_e32 v33, v33, v35
	v_fmamk_f32 v33, v33, 0x3a800000, v69
	v_mul_f32_e32 v35, 0x4f800000, v33
	v_cmp_gt_f32_e32 vcc, s14, v33
	v_mov_b32_e32 v78, v44
	v_mov_b32_e32 v82, v40
	v_cndmask_b32_e32 v33, v33, v35, vcc
	v_sqrt_f32_e32 v35, v33
	v_mov_b32_e32 v79, v72
	v_mov_b32_e32 v83, v70
	v_add_u32_e32 v44, -1, v35
	v_fma_f32 v62, -v44, v35, v33
	v_cmp_ge_f32_e64 s[2:3], 0, v62
	v_add_u32_e32 v62, 1, v35
	s_nop 0
	v_cndmask_b32_e64 v44, v35, v44, s[2:3]
	v_fma_f32 v35, -v62, v35, v33
	v_cmp_lt_f32_e64 s[2:3], 0, v35
	s_nop 1
	v_cndmask_b32_e64 v35, v44, v62, s[2:3]
	v_mul_f32_e32 v44, 0x37800000, v35
	v_cndmask_b32_e32 v35, v35, v44, vcc
	v_cmp_class_f32_e32 vcc, v33, v80
	s_nop 1
	v_cndmask_b32_e32 v35, v35, v33, vcc
	v_div_scale_f32 v44, s[2:3], v35, v35, 1.0
	v_rcp_f32_e32 v62, v44
	v_mov_b32_e32 v33, v74
	v_fma_f32 v40, -v44, v62, 1.0
	v_fmac_f32_e32 v62, v40, v62
	v_div_scale_f32 v40, vcc, 1.0, v35, 1.0
	v_mul_f32_e32 v65, v40, v62
	v_fma_f32 v68, -v44, v65, v40
	v_fmac_f32_e32 v65, v68, v62
	v_fma_f32 v40, -v44, v65, v40
	v_div_fmas_f32 v40, v40, v62, v65
	v_div_fixup_f32 v62, v40, v35, 1.0
	v_mov_b32_e32 v44, v73
	v_mov_b32_e32 v65, v63
	v_pk_mul_f32 v[78:79], v[78:79], v[62:63] op_sel_hi:[1,0]
	v_pk_mul_f32 v[44:45], v[44:45], v[62:63] op_sel_hi:[1,0]
	v_mov_b32_e32 v40, v71
	v_mov_b32_e32 v35, v42
	v_lshl_add_u64 v[76:77], v[76:77], 0, v[64:65]
	s_nop 0
	v_pk_fma_f32 v[74:75], v[2:3], v[44:45], v[30:31]
	v_pk_fma_f32 v[72:73], v[0:1], v[78:79], v[28:29]
	v_pk_mul_f32 v[44:45], v[82:83], v[62:63] op_sel_hi:[1,0]
	v_pk_mul_f32 v[40:41], v[40:41], v[62:63] op_sel_hi:[1,0]
	v_pk_mul_f32 v[36:37], v[36:37], v[62:63] op_sel_hi:[1,0]
	v_pk_mul_f32 v[38:39], v[38:39], v[62:63] op_sel_hi:[1,0]
	v_pk_mul_f32 v[32:33], v[32:33], v[62:63] op_sel_hi:[1,0]
	v_pk_mul_f32 v[34:35], v[34:35], v[62:63] op_sel_hi:[1,0]
	global_store_dwordx4 v[76:77], v[72:75], off
	v_pk_fma_f32 v[70:71], v[4:5], v[44:45], v[12:13]
	v_pk_fma_f32 v[38:39], v[10:11], v[38:39], v[18:19]
	v_pk_fma_f32 v[72:73], v[6:7], v[40:41], v[14:15]
	v_pk_fma_f32 v[36:37], v[8:9], v[36:37], v[16:17]
	v_pk_fma_f32 v[34:35], v[22:23], v[34:35], v[26:27]
	v_pk_fma_f32 v[32:33], v[20:21], v[32:33], v[24:25]
	global_store_dwordx4 v[76:77], v[70:73], off offset:1024
	global_store_dwordx4 v[76:77], v[36:39], off offset:2048
	global_store_dwordx4 v[76:77], v[32:35], off offset:3072
.Lln_bottom_stored:
	s_or_b64 exec, exec, s[8:9]
	s_and_b64 s[0:1], exec, s[0:1]
	s_or_b64 s[6:7], s[0:1], s[6:7]
	v_mov_b32_e32 v68, v43
	s_waitcnt vmcnt(7)
	v_mov_b32_e32 v44, v58
	v_mov_b32_e32 v72, v59
	v_mov_b32_e32 v73, v60
	v_mov_b32_e32 v45, v61
	s_waitcnt vmcnt(6)
	v_mov_b32_e32 v40, v54
	v_mov_b32_e32 v70, v55
	v_mov_b32_e32 v71, v56
	v_mov_b32_e32 v41, v57
	s_waitcnt vmcnt(5)
	v_mov_b32_e32 v36, v50
	v_mov_b32_e32 v37, v51
	v_mov_b32_e32 v38, v52
	v_mov_b32_e32 v39, v53
	s_waitcnt vmcnt(4)
	v_mov_b32_e32 v32, v46
	v_mov_b32_e32 v74, v47
	v_mov_b32_e32 v34, v48
	v_mov_b32_e32 v42, v49
	s_andn2_b64 exec, exec, s[6:7]
	s_cbranch_execz .LBB0_1827
	s_branch .LBB0_1819
